# P0: in-projection and memory K/V weight transposes by a hand-written routine (all loads of an item in flight, one LDS pass) instead of the compiler's item loop
# speedup vs baseline: 1.0258x; 1.0258x over previous
; #define LAS __attribute__((address_space(3)))
; __device__ __forceinline__ void tr_item(const float* W, int ldw, int K, int k0, int sc0, bf16* WT, int dr0, const float* gain, float cs, LAS float* scr, int lane) {
; #pragma unroll 16
;     for (int i = 0; i < 32; ++i) { const int kk = 2 * i + (lane >> 5); const float g = gain ? gain[k0 + kk] * cs : cs;
;         scr[kk * 33 + (lane & 31)] = W[(size_t)(k0 + kk) * ldw + sc0 + (lane & 31)] * g; }
; __global__ void __launch_bounds__(NTHR, 2) hybrid_fwd(Args args) {
;     ...
;         for (int it = gw; it < NIT; it += NGW) {
;             int r = it;
;             if (r < I0) { const int kb = r / 128, nb = r % 128, n0 = 32 * nb; tr_item(w_in, INC, 1024, 64 * kb, n0 < 2048 ? n0 : n0 + 8, W1t, n0, norm_mix_g, 1.0f, scr, lane); continue; } r -= I0;
.LBB0_14:
	s_load_dwordx4 s[16:19], s[0:1], 0xa0
	s_load_dwordx2 s[8:9], s[0:1], 0x0
	s_load_dwordx2 s[30:31], s[0:1], 0x8
	s_load_dwordx2 s[6:7], s[0:1], 0x10
	s_load_dwordx2 s[10:11], s[0:1], 0x18
	s_load_dwordx2 s[14:15], s[0:1], 0x20
	s_load_dwordx2 s[12:13], s[0:1], 0x30
	s_load_dwordx2 s[34:35], s[0:1], 0x38
	s_load_dwordx2 s[36:37], s[0:1], 0x40
	s_load_dwordx2 s[52:53], s[0:1], 0x48
	s_load_dwordx2 s[58:59], s[0:1], 0x50
	s_load_dwordx2 s[38:39], s[0:1], 0x58
	s_load_dwordx2 s[40:41], s[0:1], 0x60
	s_load_dwordx2 s[4:5], s[0:1], 0x68
	s_load_dwordx2 s[54:55], s[0:1], 0x70
	s_load_dwordx2 s[48:49], s[0:1], 0x78
	s_load_dwordx2 s[42:43], s[0:1], 0x80
	s_load_dwordx2 s[56:57], s[0:1], 0x88
	s_load_dwordx2 s[46:47], s[0:1], 0x90
	s_load_dwordx2 s[50:51], s[0:1], 0x98
	s_mov_b32 s44, s20
	s_mov_b32 s60, s2
	s_lshr_b32 s74, s72, 6
	v_mbcnt_hi_u32_b32 v212, -1, v0
	s_lshl_b32 s3, s60, 3
	s_add_i32 s26, s3, s74
	s_lshl_b32 s28, s44, 3
	s_mov_b32 s45, 0
	v_mov_b32_e32 v32, v212
	s_waitcnt lgkmcnt(0)
	s_mov_b64 s[24:25], s[18:19]
	s_cmpk_gt_i32 s26, 0x1f7f
	v_ashrrev_i32_e32 v0, 3, v32
	s_cbranch_scc1 .LBB0_186
	s_cmp_eq_u32 s20, 0x100
	s_cbranch_scc0 .Lp0t_orig
	v_lshrrev_b32_e32 v176, 5, v212
	v_and_b32_e32 v177, 31, v212
	v_lshlrev_b32_e32 v177, 2, v177
	v_and_b32_e32 v178, 7, v212
	v_lshlrev_b32_e32 v178, 4, v178
	v_lshrrev_b32_e32 v179, 3, v212
	v_lshlrev_b32_e32 v181, 2, v176
	s_lshl_b32 s79, s74, 14
	v_mul_u32_u24_e32 v182, 0x84, v176
	v_add3_u32 v182, v182, v177, s79
	v_and_b32_e32 v183, 7, v212
	v_mul_u32_u24_e32 v183, 0x420, v183
	v_lshl_add_u32 v183, v179, 2, v183
	v_add_u32_e32 v183, s79, v183
	s_lshl_b32 s78, s2, 3
	s_add_i32 s78, s78, s74
	s_mov_b32 s77, s78
.Lp0t_item:
	s_cmp_ge_u32 s77, 2560
	s_cbranch_scc1 .Lp0t_done
	s_cmp_ge_u32 s77, 2048
	s_cbranch_scc1 .Lp0t_m1
	s_sub_i32 s60, s77, 0
	s_load_dwordx2 s[38:39], s[0:1], 0x18
	s_load_dwordx2 s[42:43], s[0:1], 0x10
	s_mov_b32 s41, 0x4020
	s_mov_b32 s67, 0x800
	s_mov_b32 s68, 0x3f800000
	s_add_u32 s46, s18, 0x100000
	s_addc_u32 s47, s19, 0
	s_lshr_b32 s61, s60, 7
	s_and_b32 s62, s60, 127
	s_lshl_b32 s63, s61, 6
	s_lshl_b32 s64, s62, 5
	s_cmp_ge_u32 s64, 0x800
	s_cselect_b32 s66, 8, 0
	s_add_i32 s66, s66, s64
	s_branch .Lp0t_decoded
.Lp0t_m1:
	s_sub_i32 s60, s77, 2048
	s_load_dwordx2 s[38:39], s[0:1], 0x70
	s_load_dwordx2 s[42:43], s[0:1], 0x60
	s_mov_b32 s41, 0x1000
	s_mov_b32 s67, 0x800
	s_mov_b32 s68, 0x3f800000
	s_add_u32 s46, s18, 0xe00000
	s_addc_u32 s47, s19, 0
	s_lshr_b32 s61, s60, 5
	s_and_b32 s62, s60, 31
	s_lshl_b32 s63, s61, 6
	s_lshl_b32 s64, s62, 5
	s_mov_b32 s66, s64
.Lp0t_decoded:
	s_waitcnt lgkmcnt(0)
	s_mul_i32 s79, s63, s41
	s_lshl_b32 s88, s66, 2
	s_add_u32 s79, s79, s88
	s_add_u32 s82, s38, s79
	s_addc_u32 s83, s39, 0
	s_lshl_b32 s89, s41, 1
	v_mad_u32_u24 v180, v176, s41, v177
	global_load_dword v96, v180, s[82:83] nt
	s_add_u32 s82, s82, s89
	s_addc_u32 s83, s83, 0
	global_load_dword v97, v180, s[82:83] nt
	s_add_u32 s82, s82, s89
	s_addc_u32 s83, s83, 0
	global_load_dword v98, v180, s[82:83] nt
	s_add_u32 s82, s82, s89
	s_addc_u32 s83, s83, 0
	global_load_dword v99, v180, s[82:83] nt
	s_add_u32 s82, s82, s89
	s_addc_u32 s83, s83, 0
	global_load_dword v100, v180, s[82:83] nt
	s_add_u32 s82, s82, s89
	s_addc_u32 s83, s83, 0
	global_load_dword v101, v180, s[82:83] nt
	s_add_u32 s82, s82, s89
	s_addc_u32 s83, s83, 0
	global_load_dword v102, v180, s[82:83] nt
	s_add_u32 s82, s82, s89
	s_addc_u32 s83, s83, 0
	global_load_dword v103, v180, s[82:83] nt
	s_add_u32 s82, s82, s89
	s_addc_u32 s83, s83, 0
	global_load_dword v104, v180, s[82:83] nt
	s_add_u32 s82, s82, s89
	s_addc_u32 s83, s83, 0
	global_load_dword v105, v180, s[82:83] nt
	s_add_u32 s82, s82, s89
	s_addc_u32 s83, s83, 0
	global_load_dword v106, v180, s[82:83] nt
	s_add_u32 s82, s82, s89
	s_addc_u32 s83, s83, 0
	global_load_dword v107, v180, s[82:83] nt
	s_add_u32 s82, s82, s89
	s_addc_u32 s83, s83, 0
	global_load_dword v108, v180, s[82:83] nt
	s_add_u32 s82, s82, s89
	s_addc_u32 s83, s83, 0
	global_load_dword v109, v180, s[82:83] nt
	s_add_u32 s82, s82, s89
	s_addc_u32 s83, s83, 0
	global_load_dword v110, v180, s[82:83] nt
	s_add_u32 s82, s82, s89
	s_addc_u32 s83, s83, 0
	global_load_dword v111, v180, s[82:83] nt
	s_add_u32 s82, s82, s89
	s_addc_u32 s83, s83, 0
	global_load_dword v112, v180, s[82:83] nt
	s_add_u32 s82, s82, s89
	s_addc_u32 s83, s83, 0
	global_load_dword v113, v180, s[82:83] nt
	s_add_u32 s82, s82, s89
	s_addc_u32 s83, s83, 0
	global_load_dword v114, v180, s[82:83] nt
	s_add_u32 s82, s82, s89
	s_addc_u32 s83, s83, 0
	global_load_dword v115, v180, s[82:83] nt
	s_add_u32 s82, s82, s89
	s_addc_u32 s83, s83, 0
	global_load_dword v116, v180, s[82:83] nt
	s_add_u32 s82, s82, s89
	s_addc_u32 s83, s83, 0
	global_load_dword v117, v180, s[82:83] nt
	s_add_u32 s82, s82, s89
	s_addc_u32 s83, s83, 0
	global_load_dword v118, v180, s[82:83] nt
	s_add_u32 s82, s82, s89
	s_addc_u32 s83, s83, 0
	global_load_dword v119, v180, s[82:83] nt
	s_add_u32 s82, s82, s89
	s_addc_u32 s83, s83, 0
	global_load_dword v120, v180, s[82:83] nt
	s_add_u32 s82, s82, s89
	s_addc_u32 s83, s83, 0
	global_load_dword v121, v180, s[82:83] nt
	s_add_u32 s82, s82, s89
	s_addc_u32 s83, s83, 0
	global_load_dword v122, v180, s[82:83] nt
	s_add_u32 s82, s82, s89
	s_addc_u32 s83, s83, 0
	global_load_dword v123, v180, s[82:83] nt
	s_add_u32 s82, s82, s89
	s_addc_u32 s83, s83, 0
	global_load_dword v124, v180, s[82:83] nt
	s_add_u32 s82, s82, s89
	s_addc_u32 s83, s83, 0
	global_load_dword v125, v180, s[82:83] nt
	s_add_u32 s82, s82, s89
	s_addc_u32 s83, s83, 0
	global_load_dword v126, v180, s[82:83] nt
	s_add_u32 s82, s82, s89
; #define LAS __attribute__((address_space(3)))
; __device__ __forceinline__ void tr_item(const float* W, int ldw, int K, int k0, int sc0, bf16* WT, int dr0, const float* gain, float cs, LAS float* scr, int lane) {
; #pragma unroll 16
;     for (int i = 0; i < 32; ++i) { const int kk = 2 * i + (lane >> 5); const float g = gain ? gain[k0 + kk] * cs : cs;
;         scr[kk * 33 + (lane & 31)] = W[(size_t)(k0 + kk) * ldw + sc0 + (lane & 31)] * g; }
;     asm volatile("s_waitcnt lgkmcnt(0)" ::: "memory");
	s_addc_u32 s83, s83, 0
	global_load_dword v127, v180, s[82:83] nt
	s_lshl_b32 s79, s63, 2
	s_add_u32 s84, s42, s79
	s_addc_u32 s85, s43, 0
	global_load_dword v128, v181, s[84:85] offset:0
	global_load_dword v129, v181, s[84:85] offset:8
	global_load_dword v130, v181, s[84:85] offset:16
	global_load_dword v131, v181, s[84:85] offset:24
	global_load_dword v132, v181, s[84:85] offset:32
	global_load_dword v133, v181, s[84:85] offset:40
	global_load_dword v134, v181, s[84:85] offset:48
	global_load_dword v135, v181, s[84:85] offset:56
	global_load_dword v136, v181, s[84:85] offset:64
	global_load_dword v137, v181, s[84:85] offset:72
	global_load_dword v138, v181, s[84:85] offset:80
	global_load_dword v139, v181, s[84:85] offset:88
	global_load_dword v140, v181, s[84:85] offset:96
	global_load_dword v141, v181, s[84:85] offset:104
	global_load_dword v142, v181, s[84:85] offset:112
	global_load_dword v143, v181, s[84:85] offset:120
	global_load_dword v144, v181, s[84:85] offset:128
	global_load_dword v145, v181, s[84:85] offset:136
	global_load_dword v146, v181, s[84:85] offset:144
	global_load_dword v147, v181, s[84:85] offset:152
	global_load_dword v148, v181, s[84:85] offset:160
	global_load_dword v149, v181, s[84:85] offset:168
	global_load_dword v150, v181, s[84:85] offset:176
	global_load_dword v151, v181, s[84:85] offset:184
	global_load_dword v152, v181, s[84:85] offset:192
	global_load_dword v153, v181, s[84:85] offset:200
	global_load_dword v154, v181, s[84:85] offset:208
	global_load_dword v155, v181, s[84:85] offset:216
	global_load_dword v156, v181, s[84:85] offset:224
	global_load_dword v157, v181, s[84:85] offset:232
	global_load_dword v158, v181, s[84:85] offset:240
	global_load_dword v159, v181, s[84:85] offset:248
	s_waitcnt vmcnt(0)
	v_mul_f32_e32 v128, s68, v128
	v_mul_f32_e32 v129, s68, v129
	v_mul_f32_e32 v130, s68, v130
	v_mul_f32_e32 v131, s68, v131
	v_mul_f32_e32 v132, s68, v132
	v_mul_f32_e32 v133, s68, v133
	v_mul_f32_e32 v134, s68, v134
	v_mul_f32_e32 v135, s68, v135
	v_mul_f32_e32 v136, s68, v136
	v_mul_f32_e32 v137, s68, v137
	v_mul_f32_e32 v138, s68, v138
	v_mul_f32_e32 v139, s68, v139
	v_mul_f32_e32 v140, s68, v140
	v_mul_f32_e32 v141, s68, v141
	v_mul_f32_e32 v142, s68, v142
	v_mul_f32_e32 v143, s68, v143
	v_mul_f32_e32 v144, s68, v144
	v_mul_f32_e32 v145, s68, v145
	v_mul_f32_e32 v146, s68, v146
	v_mul_f32_e32 v147, s68, v147
	v_mul_f32_e32 v148, s68, v148
	v_mul_f32_e32 v149, s68, v149
	v_mul_f32_e32 v150, s68, v150
	v_mul_f32_e32 v151, s68, v151
	v_mul_f32_e32 v152, s68, v152
	v_mul_f32_e32 v153, s68, v153
	v_mul_f32_e32 v154, s68, v154
	v_mul_f32_e32 v155, s68, v155
	v_mul_f32_e32 v156, s68, v156
	v_mul_f32_e32 v157, s68, v157
	v_mul_f32_e32 v158, s68, v158
	v_mul_f32_e32 v159, s68, v159
	v_mul_f32_e32 v96, v96, v128
	v_mul_f32_e32 v97, v97, v129
	v_mul_f32_e32 v98, v98, v130
	v_mul_f32_e32 v99, v99, v131
	v_mul_f32_e32 v100, v100, v132
	v_mul_f32_e32 v101, v101, v133
	v_mul_f32_e32 v102, v102, v134
	v_mul_f32_e32 v103, v103, v135
	v_mul_f32_e32 v104, v104, v136
	v_mul_f32_e32 v105, v105, v137
	v_mul_f32_e32 v106, v106, v138
	v_mul_f32_e32 v107, v107, v139
	v_mul_f32_e32 v108, v108, v140
	v_mul_f32_e32 v109, v109, v141
	v_mul_f32_e32 v110, v110, v142
	v_mul_f32_e32 v111, v111, v143
	v_mul_f32_e32 v112, v112, v144
	v_mul_f32_e32 v113, v113, v145
	v_mul_f32_e32 v114, v114, v146
	v_mul_f32_e32 v115, v115, v147
	v_mul_f32_e32 v116, v116, v148
	v_mul_f32_e32 v117, v117, v149
	v_mul_f32_e32 v118, v118, v150
	v_mul_f32_e32 v119, v119, v151
	v_mul_f32_e32 v120, v120, v152
	v_mul_f32_e32 v121, v121, v153
	v_mul_f32_e32 v122, v122, v154
	v_mul_f32_e32 v123, v123, v155
	v_mul_f32_e32 v124, v124, v156
	v_mul_f32_e32 v125, v125, v157
	v_mul_f32_e32 v126, v126, v158
	v_mul_f32_e32 v127, v127, v159
	ds_write_b32 v182, v96 offset:0
	ds_write_b32 v182, v97 offset:264
	ds_write_b32 v182, v98 offset:528
	ds_write_b32 v182, v99 offset:792
	ds_write_b32 v182, v100 offset:1056
	ds_write_b32 v182, v101 offset:1320
	ds_write_b32 v182, v102 offset:1584
	ds_write_b32 v182, v103 offset:1848
	ds_write_b32 v182, v104 offset:2112
	ds_write_b32 v182, v105 offset:2376
	ds_write_b32 v182, v106 offset:2640
	ds_write_b32 v182, v107 offset:2904
	ds_write_b32 v182, v108 offset:3168
	ds_write_b32 v182, v109 offset:3432
	ds_write_b32 v182, v110 offset:3696
	ds_write_b32 v182, v111 offset:3960
	ds_write_b32 v182, v112 offset:4224
	ds_write_b32 v182, v113 offset:4488
	ds_write_b32 v182, v114 offset:4752
	ds_write_b32 v182, v115 offset:5016
	ds_write_b32 v182, v116 offset:5280
	ds_write_b32 v182, v117 offset:5544
	ds_write_b32 v182, v118 offset:5808
	ds_write_b32 v182, v119 offset:6072
	ds_write_b32 v182, v120 offset:6336
	ds_write_b32 v182, v121 offset:6600
	ds_write_b32 v182, v122 offset:6864
	ds_write_b32 v182, v123 offset:7128
	ds_write_b32 v182, v124 offset:7392
	ds_write_b32 v182, v125 offset:7656
	ds_write_b32 v182, v126 offset:7920
	ds_write_b32 v182, v127 offset:8184
	s_waitcnt lgkmcnt(0)
; #define LAS __attribute__((address_space(3)))
; __device__ __forceinline__ unsigned pk2(float lo, float hi) { return pg8::cvt_pk_bf16(lo, hi); }
; __device__ __forceinline__ void tr_item(const float* W, int ldw, int K, int k0, int sc0, bf16* WT, int dr0, const float* gain, float cs, LAS float* scr, int lane) {
;     ...
;     const int c = lane & 7;
; #pragma unroll
;     for (int j = 0; j < 4; ++j) { const int n = (lane >> 3) + 8 * j; const LAS float* s = scr + (8 * c) * 33 + n;
;         u32x4 o; o.x = pk2(s[0 * 33], s[1 * 33]); o.y = pk2(s[2 * 33], s[3 * 33]); o.z = pk2(s[4 * 33], s[5 * 33]); o.w = pk2(s[6 * 33], s[7 * 33]);
;         *(u32x4*)(WT + (size_t)(dr0 + n) * K + k0 + 8 * c) = o; }
;     asm volatile("s_waitcnt lgkmcnt(0)" ::: "memory");
	s_mul_i32 s79, s64, s67
	s_lshl_b32 s88, s63, 1
	s_add_u32 s79, s79, s88
	s_add_u32 s86, s46, s79
	s_addc_u32 s87, s47, 0
	s_lshl_b32 s89, s67, 3
	v_mad_u32_u24 v184, v179, s67, v178
	ds_read2_b32 v[160:161], v183 offset0:0 offset1:33
	ds_read2_b32 v[162:163], v183 offset0:66 offset1:99
	ds_read2_b32 v[164:165], v183 offset0:132 offset1:165
	ds_read2_b32 v[166:167], v183 offset0:198 offset1:231
	s_waitcnt lgkmcnt(0)
	v_cvt_pk_bf16_f32 v168, v160, v161
	v_cvt_pk_bf16_f32 v169, v162, v163
	v_cvt_pk_bf16_f32 v170, v164, v165
	v_cvt_pk_bf16_f32 v171, v166, v167
	global_store_dwordx4 v184, v[168:171], s[86:87]
	s_add_u32 s86, s86, s89
	s_addc_u32 s87, s87, 0
	s_nop 1
	ds_read2_b32 v[160:161], v183 offset0:8 offset1:41
	ds_read2_b32 v[162:163], v183 offset0:74 offset1:107
	ds_read2_b32 v[164:165], v183 offset0:140 offset1:173
	ds_read2_b32 v[166:167], v183 offset0:206 offset1:239
	s_waitcnt lgkmcnt(0)
	v_cvt_pk_bf16_f32 v168, v160, v161
	v_cvt_pk_bf16_f32 v169, v162, v163
	v_cvt_pk_bf16_f32 v170, v164, v165
	v_cvt_pk_bf16_f32 v171, v166, v167
	global_store_dwordx4 v184, v[168:171], s[86:87]
	s_add_u32 s86, s86, s89
	s_addc_u32 s87, s87, 0
	s_nop 1
	ds_read2_b32 v[160:161], v183 offset0:16 offset1:49
	ds_read2_b32 v[162:163], v183 offset0:82 offset1:115
	ds_read2_b32 v[164:165], v183 offset0:148 offset1:181
	ds_read2_b32 v[166:167], v183 offset0:214 offset1:247
	s_waitcnt lgkmcnt(0)
	v_cvt_pk_bf16_f32 v168, v160, v161
	v_cvt_pk_bf16_f32 v169, v162, v163
	v_cvt_pk_bf16_f32 v170, v164, v165
	v_cvt_pk_bf16_f32 v171, v166, v167
	global_store_dwordx4 v184, v[168:171], s[86:87]
	s_add_u32 s86, s86, s89
	s_addc_u32 s87, s87, 0
	s_nop 1
	ds_read2_b32 v[160:161], v183 offset0:24 offset1:57
	ds_read2_b32 v[162:163], v183 offset0:90 offset1:123
	ds_read2_b32 v[164:165], v183 offset0:156 offset1:189
	ds_read2_b32 v[166:167], v183 offset0:222 offset1:255
	s_waitcnt lgkmcnt(0)
	v_cvt_pk_bf16_f32 v168, v160, v161
	v_cvt_pk_bf16_f32 v169, v162, v163
	v_cvt_pk_bf16_f32 v170, v164, v165
	v_cvt_pk_bf16_f32 v171, v166, v167
	global_store_dwordx4 v184, v[168:171], s[86:87]
	s_waitcnt lgkmcnt(0)
	s_addk_i32 s77, 0x800
	s_branch .Lp0t_item

; #define LAS __attribute__((address_space(3)))
; __device__ __forceinline__ void tr_item(const float* W, int ldw, int K, int k0, int sc0, bf16* WT, int dr0, const float* gain, float cs, LAS float* scr, int lane) {
; #pragma unroll 16
;     for (int i = 0; i < 32; ++i) { const int kk = 2 * i + (lane >> 5); const float g = gain ? gain[k0 + kk] * cs : cs;
;         scr[kk * 33 + (lane & 31)] = W[(size_t)(k0 + kk) * ldw + sc0 + (lane & 31)] * g; }
; __global__ void __launch_bounds__(NTHR, 2) hybrid_fwd(Args args) {
;     ...
;         for (int it = gw; it < NIT; it += NGW) {
;             int r = it;
;             if (r < I0) { const int kb = r / 128, nb = r % 128, n0 = 32 * nb; tr_item(w_in, INC, 1024, 64 * kb, n0 < 2048 ? n0 : n0 + 8, W1t, n0, norm_mix_g, 1.0f, scr, lane); continue; } r -= I0;
;             if (r < I1) { const int kb = r / 32, nb = r % 32; tr_item(w_fox_out, 1024, 1024, 64 * kb, 32 * nb, Wmix + 512, 32 * nb, nullptr, 1.0f, scr, lane); continue; } r -= I1;
;             if (r < I2) { const int kb = r / 32, nb = r % 32; tr_item(w_out, 1024, 1024, 64 * kb, 32 * nb, Wout, 32 * nb, nullptr, 1.0f, scr, lane); continue; } r -= I2;
;             if (r < I3) { const int kb = r / 16, nb = r % 16; tr_item(w_xq, 512, 1024, 64 * kb, 32 * nb, Wxq, 32 * nb, norm_x_g, 0.08838834764831845f * LOG2E, scr, lane); continue; } r -= I3;
;             if (r < I4) { const int kb = r / 32, nb = r % 32; tr_item(w_xkv, 1024, 1024, 64 * kb, 32 * nb, Wxkv, 32 * nb, norm_mem_g, 1.0f, scr, lane); continue; } r -= I4;
;             if (r < I5) { const int kb = r / 32, nb = r % 32; tr_item(w_xo, 1024, 512, 64 * kb, 32 * nb, Wxo, 32 * nb, nullptr, 1.0f, scr, lane); continue; } r -= I5;
;             if (r < I6) { const int kb = r / 176, nb = r % 176, n0 = 32 * nb, j = n0 >> 8, wi = n0 & 255; const int sc = wi < 128 ? 128 * j + wi : DFF + 128 * j + (wi - 128);
;                           tr_item(w_ffn_in, 2 * DFF, 1024, 64 * kb, sc, Wffi, n0, norm_ffn_g, 1.0f, scr, lane); continue; } r -= I6;
;             { const int kb = r / 32, nb = r % 32; tr_item(w_ffn_out, 1024, DFF, 64 * kb, 32 * nb, Wffo, 32 * nb, nullptr, 1.0f, scr, lane); }
.Lp0t_orig:
	v_lshlrev_b32_e32 v1, 2, v32
	v_and_b32_e32 v44, 0x7c, v1
	v_lshlrev_b32_e32 v1, 3, v32
	s_lshl_b32 s27, s74, 14
	v_mov_b32_e32 v45, 0
	v_and_b32_e32 v1, 56, v1
	s_add_i32 s3, s27, 0
	v_lshlrev_b32_e32 v6, 1, v1
	v_mov_b32_e32 v7, v45
	v_lshl_add_u64 v[4:5], s[46:47], 0, v[44:45]
	v_lshl_add_u64 v[26:27], s[24:25], 0, v[6:7]
	s_mov_b64 s[46:47], 0x1c00000
	s_cmp_lg_u64 s[42:43], 0
	v_lshl_add_u64 v[6:7], v[26:27], 0, s[46:47]
	s_cselect_b64 s[46:47], -1, 0
	s_mov_b64 s[50:51], 0x1100000
	v_lshl_add_u64 v[10:11], s[48:49], 0, v[44:45]
	s_mov_b64 s[48:49], 0x1000000
	s_cmp_lg_u64 s[40:41], 0
	v_lshl_add_u64 v[8:9], v[26:27], 0, s[50:51]
	v_lshl_add_u64 v[12:13], v[26:27], 0, s[48:49]
	s_cselect_b64 s[48:49], -1, 0
	s_mov_b64 s[50:51], 0xe00000
	s_cmp_lg_u64 s[38:39], 0
	v_ashrrev_i32_e32 v2, 5, v32
	v_lshl_add_u64 v[14:15], v[26:27], 0, s[50:51]
	s_cselect_b64 s[50:51], -1, 0
	v_lshl_add_u64 v[22:23], s[52:53], 0, v[44:45]
	s_mov_b64 s[52:53], 0x900400
	s_cmp_lg_u64 s[6:7], 0
	s_movk_i32 s29, 0x84
	v_mul_u32_u24_e32 v3, 0x84, v1
	v_lshlrev_b32_e32 v1, 2, v0
	s_mov_b64 s[62:63], 0xd00000
	v_lshl_add_u64 v[24:25], v[26:27], 0, s[52:53]
	s_cselect_b64 s[52:53], -1, 0
	v_ashrrev_i32_e32 v29, 31, v2
	v_mov_b32_e32 v28, v2
	v_lshl_add_u64 v[40:41], s[4:5], 0, v[44:45]
	s_lshl_b32 s4, s60, 5
	s_lshl_b32 s5, s74, 2
	v_add_u32_e32 v73, s3, v44
	v_add3_u32 v75, s3, v3, v1
	v_lshl_add_u64 v[16:17], v[26:27], 0, s[62:63]
	v_lshl_add_u64 v[18:19], s[58:59], 0, v[44:45]
	s_mov_b64 s[58:59], 0xb00000
	s_lshl_b32 s3, s60, 4
	s_lshl_b32 s21, s74, 1
	v_mul_lo_u32 v118, v2, s29
	v_lshlrev_b64 v[34:35], 2, v[28:29]
	v_lshl_add_u64 v[36:37], s[54:55], 0, v[44:45]
	s_movk_i32 s54, 0xa008
	s_add_i32 s62, s4, s5
	s_mov_b32 s4, 0xffff5008
	v_lshl_add_u64 v[20:21], v[26:27], 0, s[58:59]
	s_mov_b64 s[58:59], 0x100000
	s_add_i32 s3, s3, s21
	v_add_u32_e32 v1, s27, v118
	s_lshl_b32 s27, s60, 8
	s_lshl_b32 s29, s74, 5
	v_lshl_add_u64 v[38:39], s[40:41], 0, v[34:35]
	s_mov_b32 s55, -1
	v_lshl_add_u64 v[42:43], s[38:39], 0, v[34:35]
	s_mov_b32 s5, -1
	v_add_u32_e32 v114, 8, v0
	v_add_u32_e32 v115, 16, v0
	v_add_u32_e32 v116, 24, v0
	v_lshl_add_u64 v[26:27], v[26:27], 0, s[58:59]
	v_add_u32_e32 v117, 0xffffcc00, v2
	s_lshl_b32 s21, s44, 4
	v_add_u32_e32 v119, 0x108, v118
	v_add_u32_e32 v120, 0x210, v118
	v_add_u32_e32 v121, 0x318, v118
	v_add_u32_e32 v122, 0x420, v118
	v_add_u32_e32 v123, 0x528, v118
	v_add_u32_e32 v124, 0x630, v118
	v_add3_u32 v125, v1, v44, 0
	v_lshl_add_u64 v[30:31], s[56:57], 0, v[44:45]
	s_add_i32 s27, s27, s29
	s_lshl_b32 s29, s44, 8
	v_lshl_add_u64 v[38:39], v[38:39], 0, s[54:55]
	s_lshl_b32 s63, s44, 5
	v_lshl_add_u64 v[42:43], v[42:43], 0, s[4:5]
	v_lshl_add_u64 v[44:45], s[10:11], 0, v[44:45]
	s_mov_b32 s64, 0x7fffffc2
	s_movk_i32 s65, 0x1600
	s_movk_i32 s66, 0x5800
	s_mov_b64 s[54:55], 0x80
	s_movk_i32 s67, 0x4020
	s_mov_b32 s68, s3
	s_mov_b32 s69, 0
	s_mov_b32 s70, s26
	v_add_u32_e32 v126, 0x738, v118
	v_add_u32_e32 v127, 0x840, v118
	v_add_u32_e32 v128, 0x948, v118
	v_add_u32_e32 v129, 0xa50, v118
	v_add_u32_e32 v130, 0xb58, v118
	v_add_u32_e32 v131, 0xc60, v118
	v_add_u32_e32 v132, 0xd68, v118
	v_add_u32_e32 v133, 0xe70, v118
	v_add_u32_e32 v134, 0xf78, v118
	v_add_u32_e32 v135, 0x1080, v118
	v_add_u32_e32 v136, 0x1188, v118
	v_add_u32_e32 v137, 0x1290, v118
	v_add_u32_e32 v138, 0x1398, v118
	v_add_u32_e32 v139, 0x14a0, v118
	v_add_u32_e32 v140, 0x15a8, v118
	v_add_u32_e32 v141, 0x16b0, v118
	v_add_u32_e32 v142, 0x17b8, v118
	v_add_u32_e32 v143, 0x18c0, v118
	v_add_u32_e32 v144, 0x19c8, v118
	v_add_u32_e32 v145, 0x1ad0, v118
	v_add_u32_e32 v146, 0x1bd8, v118
	v_add_u32_e32 v147, 0x1ce0, v118
	v_add_u32_e32 v148, 0x1de8, v118
	v_add_u32_e32 v149, 0x1ef0, v118
	v_add_u32_e32 v150, 0x1ff8, v118
	v_add_u32_e32 v151, 0xffffe81e, v2
	v_add_u32_e32 v152, 0xffffe800, v2
	v_add_u32_e32 v153, 0xffffe81c, v2
	v_add_u32_e32 v154, 0xffffe81a, v2
	v_add_u32_e32 v155, 0xffffe818, v2
	v_add_u32_e32 v156, 0xffffe802, v2
	v_add_u32_e32 v157, 0xffffe816, v2
	v_add_u32_e32 v158, 0xffffe804, v2
	v_add_u32_e32 v159, 0xffffe814, v2
	v_add_u32_e32 v160, 0xffffe806, v2
	v_add_u32_e32 v161, 0xffffe812, v2
	v_add_u32_e32 v162, 0xffffe808, v2
	v_add_u32_e32 v163, 0xffffe810, v2
	v_add_u32_e32 v164, 0xffffe80a, v2
	v_add_u32_e32 v165, 0xffffe80e, v2
	v_add_u32_e32 v166, 0xffffe80c, v2
	v_add_u32_e32 v167, 0xffffd41e, v2
	v_add_u32_e32 v168, 0xffffd400, v2
	v_add_u32_e32 v169, 0xffffd41c, v2
	v_add_u32_e32 v170, 0xffffd41a, v2
	v_add_u32_e32 v171, 0xffffd418, v2
	v_add_u32_e32 v172, 0xffffd402, v2
	v_add_u32_e32 v173, 0xffffd416, v2
	v_add_u32_e32 v174, 0xffffd404, v2
	v_add_u32_e32 v175, 0xffffd414, v2
	v_add_u32_e32 v176, 0xffffd406, v2
	v_add_u32_e32 v177, 0xffffd412, v2
	v_add_u32_e32 v178, 0xffffd408, v2
	v_add_u32_e32 v179, 0xffffd410, v2
	v_add_u32_e32 v180, 0xffffd40a, v2
	v_add_u32_e32 v181, 0xffffd40e, v2
	v_add_u32_e32 v182, 0xffffd40c, v2
	v_add_u32_e32 v1, 2, v2
	v_add_u32_e32 v3, 6, v2
	v_add_u32_e32 v46, 4, v2
	v_add_u32_e32 v33, 10, v2
	v_add_u32_e32 v48, 8, v2
	v_add_u32_e32 v47, 14, v2
	v_add_u32_e32 v50, 12, v2
	v_add_u32_e32 v49, 18, v2
	v_add_u32_e32 v52, 16, v2
	v_add_u32_e32 v51, 22, v2
	v_add_u32_e32 v54, 20, v2
	v_add_u32_e32 v53, 26, v2
	v_add_u32_e32 v56, 24, v2
	v_add_u32_e32 v55, 30, v2
	v_add_u32_e32 v58, 28, v2
	v_add_u32_e32 v57, 34, v2
	v_add_u32_e32 v60, 32, v2
	v_add_u32_e32 v59, 38, v2
	v_add_u32_e32 v62, 36, v2
	v_add_u32_e32 v61, 42, v2
	v_add_u32_e32 v64, 40, v2
	v_add_u32_e32 v63, 46, v2
	v_add_u32_e32 v66, 44, v2
	v_add_u32_e32 v65, 50, v2
	v_add_u32_e32 v68, 48, v2
	v_add_u32_e32 v67, 54, v2
	v_add_u32_e32 v70, 52, v2
	v_add_u32_e32 v69, 58, v2
	v_add_u32_e32 v72, 56, v2
	v_add_u32_e32 v71, 62, v2
	v_add_u32_e32 v74, 60, v2
	s_branch .LBB0_18
